# v67 + retention backward pass: OF rows requested before the closing barrier of the causal-mask stage
# speedup vs baseline: 1.0097x; 1.0030x over previous
.Lre_m2:
	s_or_b64 exec, exec, s[16:17]
	v_cvt_pk_bf16_f32 v8, v112, v113
	v_cvt_pk_bf16_f32 v9, v114, v115
	ds_write_b64 v3, v[8:9]
	v_cvt_pk_bf16_f32 v12, v116, v117
	v_cvt_pk_bf16_f32 v13, v118, v119
	ds_write_b64 v3, v[12:13] offset:16
	v_cvt_pk_bf16_f32 v8, v120, v121
	v_cvt_pk_bf16_f32 v9, v122, v123
	ds_write_b64 v3, v[8:9] offset:32
	v_cvt_pk_bf16_f32 v12, v124, v125
	v_cvt_pk_bf16_f32 v13, v126, v127
	ds_write_b64 v3, v[12:13] offset:48
	s_and_b64 vcc, exec, s[46:47]
	s_cbranch_vccz .Lre_noof
	s_add_u32 s16, s40, s28
	s_addc_u32 s17, s41, s34
	s_lshl_b64 s[16:17], s[16:17], 12
	s_or_b32 s16, s16, s80
	s_add_u32 s16, s26, s16
	s_addc_u32 s17, s27, s17
	v_sub_u32_e32 v2, 0x7f, v197
	v_lshlrev_b32_e32 v3, 1, v203
	v_lshl_or_b32 v2, v2, 12, v3
	global_load_dwordx4 v[124:127], v2, s[16:17]
	v_add_u32_e32 v3, 0xfffe0000, v2
	global_load_dwordx4 v[128:131], v3, s[16:17]
	v_add_u32_e32 v4, 0xfffe0000, v3
	global_load_dwordx4 v[132:135], v4, s[16:17]
	v_add_u32_e32 v5, 0xfffe0000, v4
	global_load_dwordx4 v[136:139], v5, s[16:17]
.Lre_noof:
	s_and_b64 vcc, exec, s[56:57]
	s_waitcnt lgkmcnt(0)
	s_barrier
.LBB0_974:
.Lret_nopf:
	v_readfirstlane_b32 s16, v207
	s_cmp_eq_u32 s16, 0
	s_cbranch_scc0 .Lret_f_dg1
	ds_read_b64_tr_b16 v[2:3], v235
	ds_read_b64_tr_b16 v[4:5], v255
	ds_read_b128 v[6:9], v195
	ds_read_b128 v[10:13], v195 offset:8704
	ds_read_b64_tr_b16 v[236:237], v235 offset:4096
	ds_read_b64_tr_b16 v[238:239], v255 offset:4096
	ds_read_b128 v[240:243], v195 offset:32
	ds_read_b128 v[244:247], v195 offset:8736
	ds_read_b64_tr_b16 v[112:113], v235 offset:8192
	ds_read_b64_tr_b16 v[114:115], v255 offset:8192
	s_waitcnt lgkmcnt(6)
	v_mfma_f32_32x32x16_bf16 v[96:111], v[2:5], v[6:9], v[96:111]
	ds_read_b128 v[120:123], v195 offset:8768
	v_mfma_f32_32x32x16_bf16 v[80:95], v[2:5], v[10:13], v[80:95]
	ds_read_b64_tr_b16 v[2:3], v235 offset:12288
	ds_read_b64_tr_b16 v[4:5], v255 offset:12288
	s_waitcnt lgkmcnt(5)
	v_mfma_f32_32x32x16_bf16 v[96:111], v[236:239], v[240:243], v[96:111]
	ds_read_b128 v[10:13], v195 offset:8800
	v_mfma_f32_32x32x16_bf16 v[80:95], v[236:239], v[244:247], v[80:95]
	s_waitcnt lgkmcnt(3)
	v_mfma_f32_32x32x16_bf16 v[80:95], v[112:115], v[120:123], v[80:95]
	s_waitcnt lgkmcnt(0)
	v_mfma_f32_32x32x16_bf16 v[80:95], v[2:5], v[10:13], v[80:95]
	s_branch .Lret_f_end
